# first grid barrier: the 208 conversion workgroups arrive but do not wait (only the 48 ada-GEMM workgroups consume P0's output)
# baseline (speedup 1.0000x reference)
; __device__ __forceinline__ unsigned xb_ld(unsigned* p)              { return __hip_atomic_load(p, __ATOMIC_RELAXED, __HIP_MEMORY_SCOPE_AGENT); }
; __device__ __forceinline__ unsigned xb_add(unsigned* p, unsigned v) { return __hip_atomic_fetch_add(p, v, __ATOMIC_RELAXED, __HIP_MEMORY_SCOPE_AGENT); }
; #define XB_SPIN(cond, bar) do { unsigned _sp = 0; while (cond) { __builtin_amdgcn_s_sleep(1); \
;     if ((++_sp & 255u) == 0u) { if (xb_ld(&(bar)[XB_TMO])) break; if (_sp > XB_SPIN_CAP) { atomicAdd(&(bar)[XB_TMO], 1u); break; } } } } while (0)
; __device__ __forceinline__ void xcd_barrier(const XcdBarrier& b) {
;     ...
;         const unsigned old = xb_add(&bar[XB_XSUB(b.x)], 1u);
;         const unsigned gen = old / nloc;
;         if (old + 1u == (gen + 1u) * nloc) {
;             __builtin_amdgcn_fence(__ATOMIC_RELEASE, "agent");
;             asm volatile("s_waitcnt vmcnt(0)" ::: "memory");
;             const unsigned og = xb_add(&bar[XB_TOP], 1u);
;             const unsigned tg = og / nx;
;             if (og + 1u == (tg + 1u) * nx) xb_add(&bar[XB_TOPGEN], 1u);
;             else XB_SPIN(xb_ld(&bar[XB_TOPGEN]) == tg, bar);
;             __builtin_amdgcn_fence(__ATOMIC_ACQUIRE, "agent");
;             xb_add(&bar[XB_XGEN(b.x)], 1u);
;             asm volatile("s_waitcnt vmcnt(0)" ::: "memory");
;         } else {
;             XB_SPIN(xb_ld(&bar[XB_XGEN(b.x)]) == gen, bar);
.LBB0_54:
	s_or_b64 exec, exec, s[8:9]
	buffer_inv sc1
	v_cvt_f32_u32_e32 v4, v2
	s_waitcnt vmcnt(0)
	v_readfirstlane_b32 s0, v3
	v_sub_u32_e32 v3, 0, v2
	v_rcp_iflag_f32_e32 v4, v4
	v_add_u32_e32 v5, s0, v1
	v_mul_f32_e32 v4, 0x4f7ffffe, v4
	v_cvt_u32_f32_e32 v4, v4
	v_mul_lo_u32 v1, v3, v4
	v_mul_hi_u32 v1, v4, v1
	v_add_u32_e32 v1, v4, v1
	v_mul_hi_u32 v1, v5, v1
	v_mul_lo_u32 v3, v1, v2
	v_sub_u32_e32 v3, v5, v3
	v_add_u32_e32 v4, 1, v1
	v_cmp_ge_u32_e32 vcc, v3, v2
	s_nop 1
	v_cndmask_b32_e32 v1, v1, v4, vcc
	v_sub_u32_e32 v4, v3, v2
	v_cndmask_b32_e32 v3, v3, v4, vcc
	v_add_u32_e32 v4, 1, v1
	v_cmp_ge_u32_e32 vcc, v3, v2
	v_add_u32_e32 v3, 1, v5
	s_nop 0
	v_cndmask_b32_e32 v1, v1, v4, vcc
	v_mul_lo_u32 v4, v2, v1
	v_add_u32_e32 v2, v4, v2
	v_cmp_ne_u32_e32 vcc, v3, v2
	s_and_saveexec_b64 s[0:1], vcc
	s_xor_b64 s[0:1], exec, s[0:1]
	s_cbranch_execz .LBB0_68
	s_waitcnt lgkmcnt(0)
	s_cmp_gt_u32 s2, 47
	s_cbranch_scc0 .Lb1_wait
	s_mov_b64 s[8:9], exec
	s_branch .LBB0_67
.Lb1_wait:
	v_mov_b32_e32 v0, 0x2000
	global_load_dword v0, v0, s[6:7] offset:1024 sc1
	s_add_u32 s12, s6, 0x2400
	s_addc_u32 s13, s7, 0
	s_waitcnt vmcnt(0)
	v_cmp_eq_u32_e32 vcc, v0, v1
	s_and_saveexec_b64 s[8:9], vcc
	s_cbranch_execz .LBB0_67
	s_add_u32 s10, s84, 0xc10200
	s_addc_u32 s11, s85, 0
	s_mov_b32 s3, 1
	s_mov_b64 s[14:15], 0
	v_mov_b32_e32 v0, 0
	s_branch .LBB0_58
